# dil-merge and g3 epilogue loads batched (no per-pair drains); prologue transposes remapped so rotary/S5 workgroups take 3 items
# speedup vs baseline: 1.0168x; 1.0168x over previous
.LBB0_1217:
	s_or_b64 exec, exec, s[84:85]
	v_lshl_add_u32 v0, v115, 2, s10
	s_waitcnt lgkmcnt(0)
	s_barrier
	ds_read2st64_b32 v[78:79], v0 offset1:1
	s_and_b32 s10, s12, 0xfffff000
	s_and_b32 s84, s8, 0xfc0
	s_or_b32 s10, s10, s84
	v_mov_b64_e32 v[80:81], s[0:1]
	s_waitcnt lgkmcnt(0)
	v_add_f32_e32 v0, v78, v79
	v_fmamk_f32 v0, v0, 0x3c000000, v224
	v_cmp_gt_f32_e32 vcc, s19, v0
	v_mul_f32_e32 v78, 0x4b800000, v0
	v_mov_b32_e32 v128, v82
	v_cndmask_b32_e32 v0, v0, v78, vcc
	v_rsq_f32_e32 v0, v0
	v_mov_b32_e32 v129, v84
	v_mul_f32_e32 v78, 0x45800000, v0
	v_cndmask_b32_e32 v0, v0, v78, vcc
	v_or_b32_e32 v78, s10, v115
	s_and_b32 s10, s87, 0x180
	v_mad_i64_i32 v[80:81], s[84:85], v78, s20, v[80:81]
	s_lshl_b32 s90, s10, 2
	v_lshl_add_u64 v[80:81], v[80:81], 0, s[90:91]
	s_mov_b64 s[84:85], 0x12c01000
	v_ashrrev_i32_e32 v79, 31, v78
	v_lshl_add_u64 v[104:105], v[80:81], 0, s[84:85]
	s_add_u32 s84, s11, s90
	v_lshlrev_b64 v[106:107], 12, v[78:79]
	s_addc_u32 s85, s18, 0
	v_lshlrev_b64 v[78:79], 2, v[94:95]
	v_lshl_add_u64 v[80:81], s[84:85], 0, v[78:79]
	v_lshl_add_u64 v[78:79], v[104:105], 0, v[78:79]
	global_load_dwordx4 v[86:89], v[80:81], off
	v_pk_mul_f32 v[128:129], v[128:129], v[0:1] op_sel_hi:[1,0]
	flat_load_dwordx4 v[78:81], v[78:79]
	v_lshlrev_b64 v[166:167], 2, v[98:99]
	v_lshl_add_u64 v[168:169], s[84:85], 0, v[166:167]
	v_lshl_add_u64 v[170:171], v[104:105], 0, v[166:167]
	global_load_dwordx4 v[134:137], v[168:169], off offset:64
	global_load_dwordx4 v[138:141], v[170:171], off offset:64
	global_load_dwordx4 v[142:145], v[168:169], off offset:128
	global_load_dwordx4 v[146:149], v[170:171], off offset:128
	v_lshlrev_b64 v[166:167], 2, v[96:97]
	v_lshl_add_u64 v[168:169], s[84:85], 0, v[166:167]
	v_lshl_add_u64 v[170:171], v[104:105], 0, v[166:167]
	global_load_dwordx4 v[150:153], v[168:169], off
	global_load_dwordx4 v[154:157], v[170:171], off
	s_lshl_b32 s90, s10, 1
	s_xor_b32 s34, s34, 1
	s_waitcnt vmcnt(0)
	v_mov_b32_e32 v130, v86
	v_mov_b32_e32 v131, v88
	s_waitcnt lgkmcnt(0)
	v_mul_f32_e32 v103, 0xbfb8aa3b, v78
	v_exp_f32_e32 v108, v103
	v_mul_f32_e32 v103, 0xbfb8aa3b, v79
	v_exp_f32_e32 v110, v103
	v_mul_f32_e32 v103, 0xbfb8aa3b, v80
	v_exp_f32_e32 v109, v103
	v_mul_f32_e32 v103, 0xbfb8aa3b, v81
	v_exp_f32_e32 v111, v103
	v_pk_mul_f32 v[128:129], v[130:131], v[128:129]
	v_pk_add_f32 v[108:109], v[108:109], 1.0 op_sel_hi:[1,0]
	v_mov_b32_e32 v130, v78
	v_mov_b32_e32 v131, v80
	v_rcp_f32_e32 v109, v109
	s_nop 0
	s_nop 0
	v_mov_b32_e32 v84, v83
	v_rcp_f32_e32 v108, v108
	s_nop 0
	v_pk_mul_f32 v[82:83], v[84:85], v[0:1] op_sel_hi:[1,0]
	v_pk_add_f32 v[84:85], v[110:111], 1.0 op_sel_hi:[1,0]
	v_mov_b32_e32 v88, v87
	v_pk_mul_f32 v[82:83], v[88:89], v[82:83]
	v_pk_mul_f32 v[108:109], v[130:131], v[108:109]
	v_rcp_f32_e32 v85, v85
	s_nop 0
	v_pk_mul_f32 v[108:109], v[108:109], v[128:129]
	v_mov_b32_e32 v128, v74
	v_mov_b32_e32 v129, v76
	v_rcp_f32_e32 v84, v84
	s_nop 0
	v_mov_b32_e32 v80, v79
	v_pk_mul_f32 v[78:79], v[80:81], v[84:85]
	v_pk_mul_f32 v[78:79], v[78:79], v[82:83]
	v_cvt_pk_bf16_f32 v79, v109, v79
	v_cvt_pk_bf16_f32 v78, v108, v78
	v_lshl_add_u64 v[80:81], s[76:77], 0, v[106:107]
	v_lshl_add_u64 v[86:87], v[80:81], 0, s[90:91]
	v_lshl_add_u64 v[80:81], v[94:95], 1, v[86:87]
	flat_store_dwordx2 v[80:81], v[78:79]
	v_lshlrev_b64 v[78:79], 2, v[98:99]
	v_lshl_add_u64 v[106:107], v[104:105], 0, v[78:79]
	v_lshl_add_u64 v[88:89], s[84:85], 0, v[78:79]
	s_nop 1
	v_mov_b32_e32 v78, v138
	v_mov_b32_e32 v79, v139
	v_mov_b32_e32 v80, v140
	v_mov_b32_e32 v81, v141
	s_nop 1
	v_mov_b32_e32 v82, v134
	v_mov_b32_e32 v83, v135
	v_mov_b32_e32 v84, v136
	v_mov_b32_e32 v85, v137
	v_pk_mul_f32 v[128:129], v[128:129], v[0:1] op_sel_hi:[1,0]
	s_waitcnt lgkmcnt(0)
	v_mul_f32_e32 v103, 0xbfb8aa3b, v78
	v_exp_f32_e32 v108, v103
	v_mul_f32_e32 v103, 0xbfb8aa3b, v79
	v_exp_f32_e32 v110, v103
	v_mul_f32_e32 v103, 0xbfb8aa3b, v80
	v_exp_f32_e32 v109, v103
	v_mov_b32_e32 v130, v82
	v_mul_f32_e32 v103, 0xbfb8aa3b, v81
	v_mov_b32_e32 v131, v84
	v_pk_add_f32 v[108:109], v[108:109], 1.0 op_sel_hi:[1,0]
	v_exp_f32_e32 v111, v103
	v_pk_mul_f32 v[128:129], v[130:131], v[128:129]
	v_mov_b32_e32 v130, v78
	v_mov_b32_e32 v131, v80
	v_rcp_f32_e32 v109, v109
	s_nop 0
	s_nop 0
	v_mov_b32_e32 v76, v75
	v_rcp_f32_e32 v108, v108
	s_nop 0
	v_pk_mul_f32 v[74:75], v[76:77], v[0:1] op_sel_hi:[1,0]
	v_pk_add_f32 v[76:77], v[110:111], 1.0 op_sel_hi:[1,0]
	v_mov_b32_e32 v84, v83
	v_pk_mul_f32 v[74:75], v[84:85], v[74:75]
	v_pk_mul_f32 v[108:109], v[130:131], v[108:109]
	v_rcp_f32_e32 v77, v77
	s_nop 0
	v_pk_mul_f32 v[108:109], v[128:129], v[108:109]
	v_rcp_f32_e32 v76, v76
	s_nop 0
	v_mov_b32_e32 v80, v79
	v_pk_mul_f32 v[76:77], v[80:81], v[76:77]
	s_nop 0
	v_pk_mul_f32 v[74:75], v[74:75], v[76:77]
	v_cvt_pk_bf16_f32 v75, v109, v75
	v_cvt_pk_bf16_f32 v74, v108, v74
	v_lshl_add_u64 v[78:79], v[98:99], 1, v[86:87]
	flat_store_dwordx2 v[78:79], v[74:75] offset:32
	s_nop 1
	v_mov_b32_e32 v82, v142
	v_mov_b32_e32 v83, v143
	v_mov_b32_e32 v84, v144
	v_mov_b32_e32 v85, v145
	s_nop 0
	s_nop 1
	v_mov_b32_e32 v74, v146
	v_mov_b32_e32 v75, v147
	v_mov_b32_e32 v76, v148
	v_mov_b32_e32 v77, v149
	v_mov_b32_e32 v106, v70
	v_mov_b32_e32 v107, v72
	v_pk_mul_f32 v[106:107], v[106:107], v[0:1] op_sel_hi:[1,0]
	v_mov_b32_e32 v108, v82
	s_waitcnt lgkmcnt(0)
	v_mul_f32_e32 v81, 0xbfb8aa3b, v75
	v_mul_f32_e32 v80, 0xbfb8aa3b, v74
	v_exp_f32_e32 v88, v81
	v_mul_f32_e32 v81, 0xbfb8aa3b, v76
	v_exp_f32_e32 v80, v80
	v_exp_f32_e32 v81, v81
	v_mov_b32_e32 v109, v84
	v_mul_f32_e32 v89, 0xbfb8aa3b, v77
	v_exp_f32_e32 v89, v89
	v_pk_add_f32 v[80:81], v[80:81], 1.0 op_sel_hi:[1,0]
	v_pk_mul_f32 v[106:107], v[108:109], v[106:107]
	v_mov_b32_e32 v108, v74
	v_mov_b32_e32 v109, v76
	v_rcp_f32_e32 v81, v81
	s_nop 0
	s_nop 0
	v_mov_b32_e32 v72, v71
	v_rcp_f32_e32 v80, v80
	s_nop 0
	v_pk_mul_f32 v[70:71], v[72:73], v[0:1] op_sel_hi:[1,0]
	v_pk_add_f32 v[72:73], v[88:89], 1.0 op_sel_hi:[1,0]
	v_mov_b32_e32 v84, v83
	v_pk_mul_f32 v[70:71], v[84:85], v[70:71]
	v_pk_mul_f32 v[80:81], v[108:109], v[80:81]
	v_rcp_f32_e32 v73, v73
	s_nop 0
	v_pk_mul_f32 v[80:81], v[106:107], v[80:81]
	v_rcp_f32_e32 v72, v72
	s_nop 0
	v_mov_b32_e32 v76, v75
	v_pk_mul_f32 v[72:73], v[76:77], v[72:73]
	v_mov_b32_e32 v82, v66
	v_pk_mul_f32 v[70:71], v[70:71], v[72:73]
	v_cvt_pk_bf16_f32 v71, v81, v71
	v_cvt_pk_bf16_f32 v70, v80, v70
	v_lshlrev_b64 v[74:75], 2, v[96:97]
	flat_store_dwordx2 v[78:79], v[70:71] offset:64
	v_lshl_add_u64 v[70:71], s[84:85], 0, v[74:75]
	v_lshl_add_u64 v[74:75], v[104:105], 0, v[74:75]
	s_nop 1
	v_mov_b32_e32 v74, v154
	v_mov_b32_e32 v75, v155
	v_mov_b32_e32 v76, v156
	v_mov_b32_e32 v77, v157
	v_mov_b32_e32 v83, v68
	s_nop 1
	v_mov_b32_e32 v70, v150
	v_mov_b32_e32 v71, v151
	v_mov_b32_e32 v72, v152
	v_mov_b32_e32 v73, v153
	v_pk_mul_f32 v[82:83], v[82:83], v[0:1] op_sel_hi:[1,0]
	s_waitcnt lgkmcnt(0)
	v_mul_f32_e32 v79, 0xbfb8aa3b, v75
	v_mul_f32_e32 v78, 0xbfb8aa3b, v74
	v_exp_f32_e32 v80, v79
	v_mul_f32_e32 v79, 0xbfb8aa3b, v76
	v_exp_f32_e32 v78, v78
	v_exp_f32_e32 v79, v79
	v_mov_b32_e32 v84, v70
	v_mov_b32_e32 v85, v72
	v_pk_mul_f32 v[82:83], v[82:83], v[84:85]
	v_pk_add_f32 v[78:79], v[78:79], 1.0 op_sel_hi:[1,0]
	v_mul_f32_e32 v81, 0xbfb8aa3b, v77
	v_exp_f32_e32 v81, v81
	v_mov_b32_e32 v85, v76
	v_mov_b32_e32 v76, v75
	v_rcp_f32_e32 v79, v79
	s_nop 0
	s_nop 0
	v_mov_b32_e32 v68, v67
	v_rcp_f32_e32 v78, v78
	s_nop 0
	v_pk_mul_f32 v[66:67], v[68:69], v[0:1] op_sel_hi:[1,0]
	v_pk_add_f32 v[68:69], v[80:81], 1.0 op_sel_hi:[1,0]
	v_mov_b32_e32 v72, v71
	v_pk_mul_f32 v[66:67], v[66:67], v[72:73]
	v_mov_b32_e32 v84, v74
	v_pk_mul_f32 v[78:79], v[84:85], v[78:79]
	v_rcp_f32_e32 v69, v69
	s_nop 0
	v_pk_mul_f32 v[78:79], v[82:83], v[78:79]
	v_rcp_f32_e32 v68, v68
	s_nop 0
	v_pk_mul_f32 v[68:69], v[76:77], v[68:69]
	v_pk_mul_f32 v[66:67], v[66:67], v[68:69]
	v_cvt_pk_bf16_f32 v67, v79, v67
	v_cvt_pk_bf16_f32 v66, v78, v66
	v_lshl_add_u64 v[68:69], v[96:97], 1, v[86:87]
	s_andn2_b64 vcc, exec, s[82:83]
	flat_store_dwordx2 v[68:69], v[66:67]
	s_cbranch_vccnz .LBB0_1206
	v_sub_f32_e32 v0, v2, v10
	v_mul_f32_e32 v66, 0x3fb8aa3b, v0
	v_mul_f32_e32 v0, 0xbfb8aa3b, v0
	v_exp_f32_e32 v70, v0
	v_sub_f32_e32 v0, v3, v11
	v_mul_f32_e32 v67, 0x3fb8aa3b, v0
	v_mul_f32_e32 v0, 0xbfb8aa3b, v0
	v_exp_f32_e32 v72, v0
	v_sub_f32_e32 v0, v4, v12
	v_exp_f32_e32 v68, v67
	v_mul_f32_e32 v67, 0x3fb8aa3b, v0
	v_mul_f32_e32 v0, 0xbfb8aa3b, v0
	v_exp_f32_e32 v71, v0
	v_sub_f32_e32 v0, v5, v13
	v_mul_f32_e32 v69, 0x3fb8aa3b, v0
	v_mul_f32_e32 v0, 0xbfb8aa3b, v0
	v_exp_f32_e32 v73, v0
	v_sub_f32_e32 v0, v6, v14
	v_mul_f32_e32 v74, 0x3fb8aa3b, v0
	v_mul_f32_e32 v0, 0xbfb8aa3b, v0
	v_exp_f32_e32 v66, v66
	v_exp_f32_e32 v67, v67
	v_exp_f32_e32 v76, v0
	v_sub_f32_e32 v0, v7, v15
	v_mul_f32_e32 v75, 0x3fb8aa3b, v0
	v_mul_f32_e32 v0, 0xbfb8aa3b, v0
	v_exp_f32_e32 v69, v69
	v_exp_f32_e32 v80, v0
	v_sub_f32_e32 v0, v8, v16
	v_mov_b32_e32 v82, v18
	v_mov_b32_e32 v83, v20
	v_exp_f32_e32 v78, v75
	v_mul_f32_e32 v75, 0x3fb8aa3b, v0
	v_mul_f32_e32 v0, 0xbfb8aa3b, v0
	v_pk_mul_f32 v[82:83], v[82:83], s[36:37] op_sel_hi:[1,0]
	v_exp_f32_e32 v74, v74
	v_exp_f32_e32 v75, v75
	v_exp_f32_e32 v77, v0
	v_sub_f32_e32 v0, v9, v17
	v_pk_mul_f32 v[66:67], v[82:83], v[66:67]
	v_mov_b32_e32 v82, v19
	v_mov_b32_e32 v83, v21
	v_mul_f32_e32 v79, 0x3fb8aa3b, v0
	v_pk_mul_f32 v[82:83], v[82:83], s[36:37] op_sel_hi:[1,0]
	v_exp_f32_e32 v79, v79
	v_pk_mul_f32 v[68:69], v[82:83], v[68:69]
	v_mov_b32_e32 v82, v22
	v_mov_b32_e32 v83, v24
	v_pk_mul_f32 v[82:83], v[82:83], s[36:37] op_sel_hi:[1,0]
	v_mul_f32_e32 v0, 0xbfb8aa3b, v0
	v_pk_mul_f32 v[74:75], v[82:83], v[74:75]
	v_mov_b32_e32 v82, v23
	v_mov_b32_e32 v83, v25
	v_pk_mul_f32 v[82:83], v[82:83], s[36:37] op_sel_hi:[1,0]
	v_bfe_u32 v84, v68, 16, 1
	v_pk_mul_f32 v[78:79], v[82:83], v[78:79]
	v_exp_f32_e32 v81, v0
	v_bfe_u32 v82, v78, 16, 1
	v_bfe_u32 v0, v79, 16, 1
	v_bfe_u32 v83, v69, 16, 1
	v_add3_u32 v84, v68, v84, s23
	v_add3_u32 v68, v78, v82, s23
	v_bfe_u32 v82, v75, 16, 1
	v_add3_u32 v83, v69, v83, s23
	v_add3_u32 v0, v79, v0, s23
	v_bfe_u32 v69, v66, 16, 1
	v_bfe_u32 v78, v67, 16, 1
	v_bfe_u32 v79, v74, 16, 1
	v_add3_u32 v75, v75, v82, s23
	s_mul_i32 s10, s34, 0xd800
	v_add3_u32 v74, v74, v79, s23
	v_add3_u32 v67, v67, v78, s23
	v_add3_u32 v66, v66, v69, s23
	v_lshrrev_b32_e32 v69, 16, v75
	s_add_i32 s10, s10, 0
	v_lshrrev_b32_e32 v66, 16, v66
	v_lshrrev_b32_e32 v67, 16, v67
	v_lshrrev_b32_e32 v74, 16, v74
	v_and_or_b32 v69, v0, s15, v69
	v_lshlrev_b32_e32 v0, 1, v92
	v_and_or_b32 v68, v68, s15, v74
	v_and_or_b32 v67, v83, s15, v67
	v_and_or_b32 v66, v84, s15, v66
	v_add3_u32 v0, s10, v113, v0
	ds_write_b128 v0, v[66:69]
	v_mov_b32_e32 v68, v27
	v_mov_b32_e32 v69, v29
	v_mov_b32_e32 v66, v26
	v_mov_b32_e32 v67, v28
	v_pk_mul_f32 v[68:69], v[68:69], v[72:73]
	v_mov_b32_e32 v72, v51
	v_mov_b32_e32 v73, v53
	v_pk_mul_f32 v[66:67], v[66:67], v[70:71]
	v_mov_b32_e32 v70, v50
	v_mov_b32_e32 v71, v52
	v_pk_mul_f32 v[72:73], v[72:73], v[80:81]
	v_pk_mul_f32 v[70:71], v[70:71], v[76:77]
	v_bfe_u32 v74, v73, 16, 1
	v_bfe_u32 v75, v72, 16, 1
	v_bfe_u32 v76, v69, 16, 1
	v_bfe_u32 v77, v68, 16, 1
	v_add3_u32 v77, v68, v77, s23
	v_add3_u32 v76, v69, v76, s23
	v_add3_u32 v68, v72, v75, s23
	v_add3_u32 v69, v73, v74, s23
	v_bfe_u32 v72, v66, 16, 1
	v_bfe_u32 v73, v67, 16, 1
	v_bfe_u32 v74, v70, 16, 1
	v_bfe_u32 v75, v71, 16, 1
	v_add3_u32 v71, v71, v75, s23
	v_add3_u32 v70, v70, v74, s23
	v_add3_u32 v67, v67, v73, s23
	v_add3_u32 v66, v66, v72, s23
	v_lshrrev_b32_e32 v66, 16, v66
	v_lshrrev_b32_e32 v67, 16, v67
	v_lshrrev_b32_e32 v70, 16, v70
	v_lshrrev_b32_e32 v71, 16, v71
	v_and_or_b32 v69, v69, s15, v71
	v_and_or_b32 v68, v68, s15, v70
	v_and_or_b32 v67, v76, s15, v67
	v_and_or_b32 v66, v77, s15, v66
	ds_write_b128 v0, v[66:69] offset:9216
	v_mul_f32_e32 v0, 0x3fb8aa3b, v112
	v_exp_f32_e32 v0, v0
	v_bfe_u32 v66, v30, 16, 1
	v_add3_u32 v66, v30, v66, s23
	v_lshl_add_u32 v67, v114, 1, s10
	ds_write_b16_d16_hi v67, v66 offset:18432
	v_mul_f32_e32 v66, v0, v46
	v_bfe_u32 v68, v66, 16, 1
	v_add3_u32 v66, v66, v68, s23
	ds_write_b16_d16_hi v67, v66 offset:36864
	v_bfe_u32 v66, v31, 16, 1
	v_add3_u32 v66, v31, v66, s23
	ds_write_b16_d16_hi v67, v66 offset:18576
	v_mul_f32_e32 v66, v0, v47
	v_bfe_u32 v68, v66, 16, 1
	v_add3_u32 v66, v66, v68, s23
	ds_write_b16_d16_hi v67, v66 offset:37008
	v_bfe_u32 v66, v32, 16, 1
	v_add3_u32 v66, v32, v66, s23
	ds_write_b16_d16_hi v67, v66 offset:18720
	v_mul_f32_e32 v66, v0, v48
	v_bfe_u32 v68, v66, 16, 1
	v_add3_u32 v66, v66, v68, s23
	ds_write_b16_d16_hi v67, v66 offset:37152
	v_bfe_u32 v66, v33, 16, 1
	v_add3_u32 v66, v33, v66, s23
	ds_write_b16_d16_hi v67, v66 offset:18864
	v_mul_f32_e32 v66, v0, v49
	v_bfe_u32 v68, v66, 16, 1
	v_add3_u32 v66, v66, v68, s23
	ds_write_b16_d16_hi v67, v66 offset:37296
	v_bfe_u32 v66, v34, 16, 1
	v_add3_u32 v66, v34, v66, s23
	ds_write_b16_d16_hi v67, v66 offset:19008
	v_mul_f32_e32 v66, v0, v54
	v_bfe_u32 v68, v66, 16, 1
	v_add3_u32 v66, v66, v68, s23
	ds_write_b16_d16_hi v67, v66 offset:37440
	v_bfe_u32 v66, v35, 16, 1
	v_add3_u32 v66, v35, v66, s23
	ds_write_b16_d16_hi v67, v66 offset:19152
	v_mul_f32_e32 v66, v0, v55
	v_bfe_u32 v68, v66, 16, 1
	v_add3_u32 v66, v66, v68, s23
	ds_write_b16_d16_hi v67, v66 offset:37584
	v_bfe_u32 v66, v36, 16, 1
	v_add3_u32 v66, v36, v66, s23
	ds_write_b16_d16_hi v67, v66 offset:19296
	v_mul_f32_e32 v66, v0, v56
	v_bfe_u32 v68, v66, 16, 1
	v_add3_u32 v66, v66, v68, s23
	ds_write_b16_d16_hi v67, v66 offset:37728
	v_bfe_u32 v66, v37, 16, 1
	v_add3_u32 v66, v37, v66, s23
	ds_write_b16_d16_hi v67, v66 offset:19440
	v_mul_f32_e32 v66, v0, v57
	v_bfe_u32 v68, v66, 16, 1
	v_add3_u32 v66, v66, v68, s23
	ds_write_b16_d16_hi v67, v66 offset:37872
	v_bfe_u32 v66, v38, 16, 1
	v_add3_u32 v66, v38, v66, s23
	ds_write_b16_d16_hi v67, v66 offset:19584
	v_mul_f32_e32 v66, v0, v58
	v_bfe_u32 v68, v66, 16, 1
	v_add3_u32 v66, v66, v68, s23
	ds_write_b16_d16_hi v67, v66 offset:38016
	v_bfe_u32 v66, v39, 16, 1
	v_add3_u32 v66, v39, v66, s23
	ds_write_b16_d16_hi v67, v66 offset:19728
	v_mul_f32_e32 v66, v0, v59
	v_bfe_u32 v68, v66, 16, 1
	v_add3_u32 v66, v66, v68, s23
	ds_write_b16_d16_hi v67, v66 offset:38160
	v_bfe_u32 v66, v40, 16, 1
	v_add3_u32 v66, v40, v66, s23
	ds_write_b16_d16_hi v67, v66 offset:19872
	v_mul_f32_e32 v66, v0, v60
	v_bfe_u32 v68, v66, 16, 1
	v_add3_u32 v66, v66, v68, s23
	ds_write_b16_d16_hi v67, v66 offset:38304
	v_bfe_u32 v66, v41, 16, 1
	v_add3_u32 v66, v41, v66, s23
	ds_write_b16_d16_hi v67, v66 offset:20016
	v_mul_f32_e32 v66, v0, v61
	v_bfe_u32 v68, v66, 16, 1
	v_add3_u32 v66, v66, v68, s23
	ds_write_b16_d16_hi v67, v66 offset:38448
	v_bfe_u32 v66, v42, 16, 1
	v_add3_u32 v66, v42, v66, s23
	ds_write_b16_d16_hi v67, v66 offset:20160
	v_mul_f32_e32 v66, v0, v62
	v_bfe_u32 v68, v66, 16, 1
	v_add3_u32 v66, v66, v68, s23
	ds_write_b16_d16_hi v67, v66 offset:38592
	v_bfe_u32 v66, v43, 16, 1
	v_add3_u32 v66, v43, v66, s23
	ds_write_b16_d16_hi v67, v66 offset:20304
	v_mul_f32_e32 v66, v0, v63
	v_bfe_u32 v68, v66, 16, 1
	v_add3_u32 v66, v66, v68, s23
	ds_write_b16_d16_hi v67, v66 offset:38736
	v_bfe_u32 v66, v44, 16, 1
	v_add3_u32 v66, v44, v66, s23
	ds_write_b16_d16_hi v67, v66 offset:20448
	v_mul_f32_e32 v66, v0, v64
	v_bfe_u32 v68, v66, 16, 1
	v_add3_u32 v66, v66, v68, s23
	ds_write_b16_d16_hi v67, v66 offset:38880
	v_bfe_u32 v66, v45, 16, 1
	v_add3_u32 v66, v45, v66, s23
	v_mul_f32_e32 v0, v0, v65
	ds_write_b16_d16_hi v67, v66 offset:20592
	v_bfe_u32 v66, v0, 16, 1
	v_add3_u32 v0, v0, v66, s23
	ds_write_b16_d16_hi v67, v0 offset:39024
	s_branch .LBB0_1206

.LBB0_1222:
	v_ashrrev_i32_e32 v2, 6, v4
	v_ashrrev_i32_e32 v3, 31, v2
	v_lshlrev_b64 v[6:7], 6, v[2:3]
	v_and_b32_e32 v0, 56, v4
	v_lshl_add_u64 v[8:9], s[38:39], 0, v[6:7]
	v_lshl_add_u64 v[10:11], s[40:41], 0, v[6:7]
	v_lshl_add_u64 v[6:7], s[42:43], 0, v[6:7]
	v_lshl_add_u64 v[8:9], v[8:9], 0, v[0:1]
	v_lshl_add_u64 v[10:11], v[10:11], 0, v[0:1]
	v_lshl_add_u64 v[6:7], v[6:7], 0, v[0:1]
	flat_load_dwordx2 v[8:9], v[8:9]
	s_mov_b32 s8, 0x1000000
	flat_load_dwordx2 v[10:11], v[10:11]
	v_add_u32_e32 v4, s84, v4
	flat_load_dwordx2 v[6:7], v[6:7]
	v_lshlrev_b64 v[40:41], 10, v[2:3]
	v_and_b32_e32 v42, 0x1f8, v5
	v_lshl_add_u64 v[40:41], s[6:7], 0, v[40:41]
	v_lshlrev_b32_e32 v42, 1, v42
	v_mov_b32_e32 v43, 0
	v_lshl_add_u64 v[40:41], v[40:41], 0, v[42:43]
	global_load_dwordx4 v[44:47], v[40:41], off
	s_mov_b64 s[100:101], 0x800000
	v_lshl_add_u64 v[48:49], v[40:41], 0, s[100:101]
	global_load_dwordx4 v[52:55], v[48:49], off
	s_mov_b64 s[100:101], 0x1000000
	v_lshl_add_u64 v[48:49], v[40:41], 0, s[100:101]
	global_load_dwordx4 v[56:59], v[48:49], off
	s_waitcnt vmcnt(0) lgkmcnt(0)
	v_max3_f32 v0, v8, v10, v6
	v_sub_f32_e32 v8, v8, v0
	v_mul_f32_e32 v8, 0x3fb8aa3b, v8
	v_exp_f32_e32 v14, v8
	v_sub_f32_e32 v8, v10, v0
	v_sub_f32_e32 v0, v6, v0
	v_mul_f32_e32 v8, 0x3fb8aa3b, v8
	v_mul_f32_e32 v0, 0x3fb8aa3b, v0
	v_exp_f32_e32 v17, v8
	v_exp_f32_e32 v16, v0
	v_mov_b32_e32 v10, v7
	v_fma_f32 v0, v9, v14, 0
	v_pk_mul_f32 v[6:7], v[10:11], v[16:17]
	s_nop 0
	v_add_f32_e32 v0, v7, v0
	v_add_f32_e32 v15, v6, v0
	v_lshlrev_b64 v[6:7], 10, v[2:3]
	v_and_b32_e32 v0, 0x1f8, v5
	v_lshl_add_u64 v[6:7], s[6:7], 0, v[6:7]
	v_lshlrev_b32_e32 v0, 1, v0
	v_lshl_add_u64 v[10:11], v[6:7], 0, v[0:1]
	v_mov_b32_e32 v6, v44
	v_mov_b32_e32 v7, v45
	v_mov_b32_e32 v8, v46
	v_mov_b32_e32 v9, v47
	v_lshlrev_b64 v[2:3], 12, v[2:3]
	v_lshl_add_u64 v[2:3], s[0:1], 0, v[2:3]
	v_lshl_add_u64 v[2:3], v[2:3], 0, v[0:1]
	v_add_u32_e32 v5, s12, v5
	v_lshlrev_b32_e32 v18, 16, v6
	v_and_b32_e32 v20, 0xffff0000, v6
	v_add_co_u32_e32 v6, vcc, s19, v10
	v_lshlrev_b32_e32 v19, 16, v7
	v_and_b32_e32 v21, 0xffff0000, v7
	v_addc_co_u32_e32 v7, vcc, 0, v11, vcc
	v_add_co_u32_e32 v10, vcc, s8, v10
	v_lshlrev_b32_e32 v22, 16, v8
	v_and_b32_e32 v24, 0xffff0000, v8
	v_lshlrev_b32_e32 v23, 16, v9
	v_and_b32_e32 v25, 0xffff0000, v9
	v_mov_b32_e32 v6, v52
	v_mov_b32_e32 v7, v53
	v_mov_b32_e32 v8, v54
	v_mov_b32_e32 v9, v55
	v_addc_co_u32_e32 v11, vcc, 0, v11, vcc
	v_mov_b32_e32 v10, v56
	v_mov_b32_e32 v11, v57
	v_mov_b32_e32 v12, v58
	v_mov_b32_e32 v13, v59
	v_pk_fma_f32 v[18:19], v[14:15], v[18:19], 0 op_sel_hi:[0,1,0]
	v_pk_fma_f32 v[20:21], v[14:15], v[20:21], 0 op_sel_hi:[0,1,0]
	v_mov_b32_e32 v30, v17
	v_rcp_f32_e32 v26, v15
	s_nop 0
	v_add_co_u32_e32 v2, vcc, 0x23c00000, v2
	s_mov_b32 s8, 0x7ffff
	s_nop 0
	v_addc_co_u32_e32 v3, vcc, 0, v3, vcc
	v_cmp_lt_i32_e32 vcc, s8, v4
	s_or_b64 s[44:45], vcc, s[44:45]
	v_lshlrev_b32_e32 v29, 16, v7
	v_lshlrev_b32_e32 v28, 16, v6
	v_and_b32_e32 v7, 0xffff0000, v7
	v_and_b32_e32 v6, 0xffff0000, v6
	v_pk_fma_f32 v[18:19], v[30:31], v[28:29], v[18:19] op_sel_hi:[0,1,1]
	v_pk_fma_f32 v[6:7], v[30:31], v[6:7], v[20:21] op_sel_hi:[0,1,1]
	v_lshlrev_b32_e32 v21, 16, v11
	v_lshlrev_b32_e32 v20, 16, v10
	v_pk_fma_f32 v[18:19], v[16:17], v[20:21], v[18:19] op_sel_hi:[0,1,1]
	v_and_b32_e32 v11, 0xffff0000, v11
	v_and_b32_e32 v10, 0xffff0000, v10
	v_pk_fma_f32 v[6:7], v[16:17], v[10:11], v[6:7] op_sel_hi:[0,1,1]
	v_pk_mul_f32 v[10:11], v[18:19], v[26:27] op_sel_hi:[1,0]
	v_pk_fma_f32 v[18:19], v[14:15], v[22:23], 0 op_sel_hi:[0,1,0]
	v_pk_fma_f32 v[14:15], v[14:15], v[24:25], 0 op_sel_hi:[0,1,0]
	v_lshlrev_b32_e32 v21, 16, v9
	v_lshlrev_b32_e32 v20, 16, v8
	v_and_b32_e32 v9, 0xffff0000, v9
	v_and_b32_e32 v8, 0xffff0000, v8
	v_pk_fma_f32 v[8:9], v[30:31], v[8:9], v[14:15] op_sel_hi:[0,1,1]
	v_lshlrev_b32_e32 v15, 16, v13
	v_lshlrev_b32_e32 v14, 16, v12
	v_and_b32_e32 v13, 0xffff0000, v13
	v_and_b32_e32 v12, 0xffff0000, v12
	v_pk_fma_f32 v[18:19], v[30:31], v[20:21], v[18:19] op_sel_hi:[0,1,1]
	v_pk_fma_f32 v[8:9], v[16:17], v[12:13], v[8:9] op_sel_hi:[0,1,1]
	v_pk_mul_f32 v[6:7], v[6:7], v[26:27] op_sel_hi:[1,0]
	v_pk_fma_f32 v[14:15], v[16:17], v[14:15], v[18:19] op_sel_hi:[0,1,1]
	v_pk_mul_f32 v[8:9], v[8:9], v[26:27] op_sel_hi:[1,0]
	v_pk_mul_f32 v[12:13], v[14:15], v[26:27] op_sel_hi:[1,0]
	v_cvt_pk_bf16_f32 v9, v13, v9
	v_cvt_pk_bf16_f32 v8, v12, v8
	v_cvt_pk_bf16_f32 v7, v11, v7
	v_cvt_pk_bf16_f32 v6, v10, v6
	flat_store_dwordx4 v[2:3], v[6:9] offset:2048
	s_andn2_b64 exec, exec, s[44:45]
	s_cbranch_execnz .LBB0_1222
	s_or_b64 exec, exec, s[44:45]
